# v046 + nt on the 16 read-once f32 loads of the prologue f32-to-bf16 conversion loop
# speedup vs baseline: 1.0067x; 1.0020x over previous
; __device__ __forceinline__ unsigned pk2(float lo, float hi) { return pg8::cvt_pk_bf16(lo, hi); }
; __global__ void __launch_bounds__(NTHREADS, 2) fwd_megakernel(Params p) {
;     ...
;         for (int r0 = gw * 4; r0 < NTOK; r0 += NGW * 4) {
;             f32x4 v[4][4];
; #pragma unroll
;             for (int q = 0; q < 4; ++q) { const f32x4* xr = (const f32x4*)(p.x + (size_t)(r0 + q) * DM) + lane;
; #pragma unroll
;                 for (int jj = 0; jj < 4; ++jj) v[q][jj] = xr[64 * jj]; }
;             float ssq[4];
; #pragma unroll
;             for (int q = 0; q < 4; ++q) { float ss = 0.f; unsigned long long* o8 = (unsigned long long*)(XB + (size_t)(r0 + q) * DM) + lane;
; #pragma unroll
;                 for (int jj = 0; jj < 4; ++jj) { ss += (v[q][jj][0] * v[q][jj][0] + v[q][jj][1] * v[q][jj][1]) + (v[q][jj][2] * v[q][jj][2] + v[q][jj][3] * v[q][jj][3]);
;                     o8[64 * jj] = (unsigned long long)pk2(v[q][jj][0], v[q][jj][1]) | ((unsigned long long)pk2(v[q][jj][2], v[q][jj][3]) << 32); }
;                 ssq[q] = wave_sum(ss); }
;             { const int sl = lane >= 60 ? 0 : 1 + (lane >> 2), qq = lane >= 60 ? lane - 60 : (lane & 3);
;               const float val = lane >= 60 ? (qq == 0 ? ssq[0] : qq == 1 ? ssq[1] : qq == 2 ? ssq[2] : ssq[3]) : 0.f;
;               PART[(size_t)sl * NTOK + r0 + qq] = val; }
.LBB0_97:
	global_load_dwordx4 v[60:63], v[48:49], off nt
	global_load_dwordx4 v[64:67], v[48:49], off offset:1024 nt
	global_load_dwordx4 v[68:71], v[48:49], off offset:2048 nt
	s_waitcnt lgkmcnt(3)
	global_load_dwordx4 v[34:37], v[48:49], off offset:3072 nt
	v_add_co_u32_e32 v2, vcc, 0x1000, v48
	v_lshl_add_u64 v[4:5], s[68:69], 0, v[46:47]
	s_nop 0
	v_addc_co_u32_e32 v3, vcc, 0, v49, vcc
	global_load_dwordx4 v[30:33], v[2:3], off nt
	s_waitcnt lgkmcnt(2)
	global_load_dwordx4 v[26:29], v[2:3], off offset:1024 nt
	global_load_dwordx4 v[38:41], v[2:3], off offset:2048 nt
	global_load_dwordx4 v[72:75], v[2:3], off offset:3072 nt
	v_cmp_lt_i32_e32 vcc, v53, v52
	v_add_co_u32_e64 v84, s[6:7], s22, v4
	s_waitcnt lgkmcnt(0)
	v_cndmask_b32_e32 v7, v43, v53, vcc
	v_cmp_lt_i32_e32 vcc, v54, v52
	v_lshlrev_b32_e32 v59, 2, v7
	v_addc_co_u32_e64 v85, s[6:7], 0, v5, s[6:7]
	v_cndmask_b32_e32 v8, v43, v54, vcc
	v_cmp_lt_i32_e32 vcc, v55, v52
	v_add_co_u32_e64 v50, s[6:7], s23, v4
	s_nop 0
	v_cndmask_b32_e32 v9, v43, v55, vcc
	v_cmp_lt_i32_e32 vcc, v56, v52
	v_addc_co_u32_e64 v51, s[6:7], 0, v5, s[6:7]
	s_nop 0
	v_cndmask_b32_e32 v10, v43, v56, vcc
	v_cmp_lt_i32_e32 vcc, v57, v52
	v_lshlrev_b32_e32 v88, 2, v8
	v_lshlrev_b32_e32 v89, 2, v9
	v_cndmask_b32_e32 v11, v43, v57, vcc
	v_add_co_u32_e32 v6, vcc, 0x2000, v48
	v_lshlrev_b32_e32 v90, 2, v10
	s_nop 0
	v_addc_co_u32_e32 v7, vcc, 0, v49, vcc
	global_load_dwordx4 v[76:79], v[6:7], off nt
	global_load_dwordx4 v[80:83], v[6:7], off offset:1024 nt
	global_load_dwordx4 v[22:25], v[6:7], off offset:2048 nt
	global_load_dwordx4 v[18:21], v[6:7], off offset:3072 nt
	v_add_co_u32_e32 v86, vcc, 0x3000, v48
	v_lshlrev_b32_e32 v91, 2, v11
	s_nop 0
	v_addc_co_u32_e32 v87, vcc, 0, v49, vcc
	global_load_dwordx4 v[14:17], v[86:87], off nt
	global_load_dwordx4 v[10:13], v[86:87], off offset:1024 nt
	global_load_dwordx4 v[6:9], v[86:87], off offset:2048 nt
	global_load_dwordx4 v[2:5], v[86:87], off offset:3072 nt
	v_cmp_lt_i32_e32 vcc, v58, v52
	s_mov_b32 s28, s20
	s_waitcnt vmcnt(15)
	v_cvt_pk_bf16_f32 v86, v60, v61
	v_mul_f32_e32 v92, v61, v61
	v_mul_f32_e32 v93, v63, v63
	v_cvt_pk_bf16_f32 v87, v62, v63
	s_waitcnt vmcnt(14)
	v_mul_f32_e32 v63, v65, v65
	v_mul_f32_e32 v94, v67, v67
	s_waitcnt vmcnt(13)
	v_mul_f32_e32 v95, v69, v69
	v_mul_f32_e32 v96, v71, v71
	v_fmac_f32_e32 v92, v60, v60
	v_fmac_f32_e32 v93, v62, v62
	v_fmac_f32_e32 v63, v64, v64
	v_fmac_f32_e32 v94, v66, v66
	s_waitcnt vmcnt(12)
	v_mul_f32_e32 v97, v35, v35
	v_mul_f32_e32 v98, v37, v37
	v_fmac_f32_e32 v95, v68, v68
	v_fmac_f32_e32 v96, v70, v70
	v_add_f32_e32 v62, v92, v93
	v_add_f32_e32 v63, v63, v94
	global_store_dwordx2 v[50:51], v[86:87], off offset:-4096
	v_cvt_pk_bf16_f32 v60, v64, v65
	v_fmac_f32_e32 v97, v34, v34
	v_fmac_f32_e32 v98, v36, v36
	v_add_f32_e32 v64, v95, v96
	v_add_f32_e32 v62, v62, v63
	v_add_f32_e32 v65, v97, v98
	v_add_f32_e32 v62, v62, v64
	v_add_f32_e32 v62, v62, v65
	ds_bpermute_b32 v63, v59, v62
	v_cvt_pk_bf16_f32 v61, v66, v67
	s_waitcnt vmcnt(12)
	v_mul_f32_e32 v64, v31, v31
	v_mul_f32_e32 v65, v33, v33
	s_waitcnt vmcnt(11)
	v_mul_f32_e32 v66, v27, v27
	s_waitcnt lgkmcnt(0)
	v_add_f32_e32 v62, v62, v63
	ds_bpermute_b32 v63, v88, v62
	v_mul_f32_e32 v67, v29, v29
	global_store_dwordx2 v[84:85], v[60:61], off offset:512
	v_cvt_pk_bf16_f32 v60, v68, v69
	s_waitcnt vmcnt(11)
	v_mul_f32_e32 v68, v39, v39
	v_mul_f32_e32 v69, v41, v41
	v_fmac_f32_e32 v64, v30, v30
	v_fmac_f32_e32 v65, v32, v32
	v_fmac_f32_e32 v66, v26, v26
	v_fmac_f32_e32 v67, v28, v28
	v_cvt_pk_bf16_f32 v61, v70, v71
	global_store_dwordx2 v[84:85], v[60:61], off offset:1024
	s_waitcnt lgkmcnt(0)
	v_add_f32_e32 v60, v62, v63
	v_fmac_f32_e32 v68, v38, v38
	v_fmac_f32_e32 v69, v40, v40
	v_add_f32_e32 v62, v64, v65
	v_add_f32_e32 v63, v66, v67
	v_add_f32_e32 v62, v62, v63
	v_add_f32_e32 v63, v68, v69
	v_add_f32_e32 v62, v62, v63
	s_waitcnt vmcnt(11)
	v_mul_f32_e32 v63, v73, v73
	v_mul_f32_e32 v64, v75, v75
	v_fmac_f32_e32 v63, v72, v72
	v_fmac_f32_e32 v64, v74, v74
	v_add_f32_e32 v63, v63, v64
	v_add_f32_e32 v62, v62, v63
	ds_bpermute_b32 v63, v59, v62
	v_cvt_pk_bf16_f32 v34, v34, v35
	v_cvt_pk_bf16_f32 v35, v36, v37
	global_store_dwordx2 v[84:85], v[34:35], off offset:1536
	v_cvt_pk_bf16_f32 v30, v30, v31
	s_waitcnt lgkmcnt(0)
	v_add_f32_e32 v36, v62, v63
	ds_bpermute_b32 v37, v88, v36
	v_cvt_pk_bf16_f32 v31, v32, v33
	global_store_dwordx2 v[84:85], v[30:31], off offset:2048
	v_cvt_pk_bf16_f32 v26, v26, v27
	v_cvt_pk_bf16_f32 v27, v28, v29
	s_waitcnt lgkmcnt(0)
; __device__ __forceinline__ unsigned pk2(float lo, float hi) { return pg8::cvt_pk_bf16(lo, hi); }
; __global__ void __launch_bounds__(NTHREADS, 2) fwd_megakernel(Params p) {
;     ...
;             for (int q = 0; q < 4; ++q) { float ss = 0.f; unsigned long long* o8 = (unsigned long long*)(XB + (size_t)(r0 + q) * DM) + lane;
; #pragma unroll
;                 for (int jj = 0; jj < 4; ++jj) { ss += (v[q][jj][0] * v[q][jj][0] + v[q][jj][1] * v[q][jj][1]) + (v[q][jj][2] * v[q][jj][2] + v[q][jj][3] * v[q][jj][3]);
;                     o8[64 * jj] = (unsigned long long)pk2(v[q][jj][0], v[q][jj][1]) | ((unsigned long long)pk2(v[q][jj][2], v[q][jj][3]) << 32); }
;                 ssq[q] = wave_sum(ss); }
;             { const int sl = lane >= 60 ? 0 : 1 + (lane >> 2), qq = lane >= 60 ? lane - 60 : (lane & 3);
;               const float val = lane >= 60 ? (qq == 0 ? ssq[0] : qq == 1 ? ssq[1] : qq == 2 ? ssq[2] : ssq[3]) : 0.f;
;               PART[(size_t)sl * NTOK + r0 + qq] = val; }
	v_add_f32_e32 v36, v36, v37
	ds_bpermute_b32 v37, v89, v36
	global_store_dwordx2 v[84:85], v[26:27], off offset:2560
	v_cvt_pk_bf16_f32 v26, v38, v39
	v_cvt_pk_bf16_f32 v27, v40, v41
	global_store_dwordx2 v[84:85], v[26:27], off offset:3072
	s_waitcnt lgkmcnt(0)
	v_add_f32_e32 v30, v36, v37
	ds_bpermute_b32 v31, v90, v30
	v_cvt_pk_bf16_f32 v26, v72, v73
	v_cvt_pk_bf16_f32 v27, v74, v75
	global_store_dwordx2 v[84:85], v[26:27], off offset:3584
	s_waitcnt vmcnt(15)
	v_mul_f32_e32 v27, v77, v77
	s_waitcnt lgkmcnt(0)
	v_add_f32_e32 v28, v30, v31
	ds_bpermute_b32 v29, v91, v28
	v_fmac_f32_e32 v27, v76, v76
	ds_bpermute_b32 v61, v89, v60
	v_cndmask_b32_e32 v35, v43, v58, vcc
	s_waitcnt lgkmcnt(1)
	v_add_f32_e32 v26, v28, v29
	v_mul_f32_e32 v28, v79, v79
	v_fmac_f32_e32 v28, v78, v78
	v_add_f32_e32 v27, v27, v28
	s_waitcnt vmcnt(14)
	v_mul_f32_e32 v28, v81, v81
	v_mul_f32_e32 v29, v83, v83
	v_fmac_f32_e32 v28, v80, v80
	v_fmac_f32_e32 v29, v82, v82
	v_add_f32_e32 v28, v28, v29
	v_add_f32_e32 v27, v27, v28
	s_waitcnt vmcnt(13)
	v_mul_f32_e32 v28, v23, v23
	v_mul_f32_e32 v29, v25, v25
	v_fmac_f32_e32 v28, v22, v22
	v_fmac_f32_e32 v29, v24, v24
	v_add_f32_e32 v28, v28, v29
	v_add_f32_e32 v27, v27, v28
	s_waitcnt vmcnt(12)
	v_mul_f32_e32 v28, v19, v19
	v_mul_f32_e32 v29, v21, v21
	v_fmac_f32_e32 v28, v18, v18
	v_fmac_f32_e32 v29, v20, v20
	v_add_f32_e32 v28, v28, v29
	v_add_f32_e32 v30, v27, v28
	ds_bpermute_b32 v31, v59, v30
	v_cvt_pk_bf16_f32 v28, v76, v77
	v_cvt_pk_bf16_f32 v29, v78, v79
	global_store_dwordx2 v[50:51], v[28:29], off
	v_cvt_pk_bf16_f32 v28, v80, v81
	s_waitcnt lgkmcnt(0)
	v_add_f32_e32 v30, v30, v31
	ds_bpermute_b32 v31, v88, v30
	v_cvt_pk_bf16_f32 v29, v82, v83
	global_store_dwordx2 v[50:51], v[28:29], off offset:512
	v_cvt_pk_bf16_f32 v22, v22, v23
	s_waitcnt vmcnt(13)
	v_mul_f32_e32 v23, v15, v15
	s_waitcnt lgkmcnt(0)
	v_add_f32_e32 v28, v30, v31
	v_mul_f32_e32 v30, v17, v17
	v_fmac_f32_e32 v23, v14, v14
	v_fmac_f32_e32 v30, v16, v16
	v_add_f32_e32 v23, v23, v30
	s_waitcnt vmcnt(12)
	v_mul_f32_e32 v30, v11, v11
	v_mul_f32_e32 v31, v13, v13
	v_fmac_f32_e32 v30, v10, v10
	v_fmac_f32_e32 v31, v12, v12
	v_add_f32_e32 v30, v30, v31
	v_add_f32_e32 v23, v23, v30
	s_waitcnt vmcnt(11)
	v_mul_f32_e32 v30, v7, v7
	v_mul_f32_e32 v31, v9, v9
	v_fmac_f32_e32 v30, v6, v6
	v_fmac_f32_e32 v31, v8, v8
	v_add_f32_e32 v30, v30, v31
	v_add_f32_e32 v23, v23, v30
	s_waitcnt vmcnt(10)
	v_mul_f32_e32 v30, v3, v3
	v_mul_f32_e32 v31, v5, v5
	v_fmac_f32_e32 v30, v2, v2
	v_fmac_f32_e32 v31, v4, v4
	v_add_f32_e32 v30, v30, v31
	v_add_f32_e32 v30, v23, v30
	ds_bpermute_b32 v31, v59, v30
	v_cvt_pk_bf16_f32 v23, v24, v25
	global_store_dwordx2 v[50:51], v[22:23], off offset:1024
	v_cvt_pk_bf16_f32 v18, v18, v19
	v_cvt_pk_bf16_f32 v19, v20, v21
	s_waitcnt lgkmcnt(0)
	v_add_f32_e32 v22, v30, v31
	ds_bpermute_b32 v23, v88, v22
	ds_bpermute_b32 v29, v89, v28
	v_add_f32_e32 v60, v60, v61
	ds_bpermute_b32 v61, v90, v60
	global_store_dwordx2 v[50:51], v[18:19], off offset:1536
	s_waitcnt lgkmcnt(2)
	v_add_f32_e32 v20, v22, v23
	ds_bpermute_b32 v21, v89, v20
	s_waitcnt lgkmcnt(2)
	v_add_f32_e32 v24, v28, v29
	ds_bpermute_b32 v25, v90, v24
	s_waitcnt lgkmcnt(2)
	v_add_f32_e32 v60, v60, v61
	v_cvt_pk_bf16_f32 v14, v14, v15
	s_waitcnt lgkmcnt(1)
	v_add_f32_e32 v20, v20, v21
	ds_bpermute_b32 v21, v90, v20
	s_waitcnt lgkmcnt(1)
	v_add_f32_e32 v24, v24, v25
	v_cvt_pk_bf16_f32 v15, v16, v17
	global_store_dwordx2 v[50:51], v[14:15], off offset:2048
	v_cvt_pk_bf16_f32 v10, v10, v11
	v_cvt_pk_bf16_f32 v11, v12, v13
	s_waitcnt lgkmcnt(0)
	v_add_f32_e32 v12, v20, v21
	ds_bpermute_b32 v61, v91, v60
	ds_bpermute_b32 v25, v91, v24
	ds_bpermute_b32 v13, v91, v12
	global_store_dwordx2 v[50:51], v[10:11], off offset:2560
	v_cvt_pk_bf16_f32 v6, v6, v7
	s_waitcnt lgkmcnt(2)
	v_add_f32_e32 v34, v60, v61
	v_lshlrev_b32_e32 v60, 2, v35
	s_waitcnt lgkmcnt(1)
	v_add_f32_e32 v18, v24, v25
	v_cvt_pk_bf16_f32 v7, v8, v9
	global_store_dwordx2 v[50:51], v[6:7], off offset:3072
	s_waitcnt lgkmcnt(0)
	v_add_f32_e32 v6, v12, v13
	ds_bpermute_b32 v35, v60, v34
	ds_bpermute_b32 v27, v60, v26
	ds_bpermute_b32 v19, v60, v18
	ds_bpermute_b32 v7, v60, v6
	v_cvt_pk_bf16_f32 v2, v2, v3
	v_cvt_pk_bf16_f32 v3, v4, v5
	global_store_dwordx2 v[50:51], v[2:3], off offset:3584
	v_mov_b32_e32 v2, 0
	s_and_saveexec_b64 s[6:7], s[0:1]
	s_cbranch_execz .LBB0_96
	s_waitcnt lgkmcnt(3)
	v_add_f32_e32 v2, v34, v35
	v_cmp_lt_i32_e32 vcc, 60, v1
	s_and_saveexec_b64 s[16:17], vcc
	s_cbranch_execz .LBB0_95
	v_cmp_ne_u32_e32 vcc, 61, v1
	s_and_saveexec_b64 s[20:21], vcc
	s_xor_b64 s[20:21], exec, s[20:21]
	s_cbranch_execz .LBB0_101
	s_waitcnt lgkmcnt(1)
	v_add_f32_e32 v2, v18, v19
	s_waitcnt lgkmcnt(0)
	v_add_f32_e32 v3, v6, v7
	v_cndmask_b32_e64 v2, v3, v2, s[4:5]
